# grid barrier spin loops poll without s_sleep
# baseline (speedup 1.0000x reference)
.LBB0_695:
	s_and_b32 s22, s28, 0xff
	s_mov_b64 s[20:21], -1
	s_cmp_lg_u32 s22, 0
	s_mov_b64 s[22:23], -1
	s_nop 0
	s_cbranch_scc1 .LBB0_699
	v_mov_b64_e32 v[2:3], s[6:7]
	flat_load_dword v0, v[2:3] offset:512 sc1
	s_mov_b64 s[22:23], 0
	s_mov_b64 s[24:25], -1
	s_waitcnt vmcnt(0) lgkmcnt(0)
	v_cmp_eq_u32_e32 vcc, 0, v0
	s_and_saveexec_b64 s[26:27], vcc
	s_cmp_lt_u32 s28, 0x400001
	s_cselect_b64 s[22:23], -1, 0
	s_xor_b64 s[24:25], exec, -1
	s_and_b64 s[22:23], s[22:23], exec
	s_or_b64 exec, exec, s[26:27]

.LBB0_709:
	s_and_b32 s22, s28, 0xff
	s_mov_b64 s[20:21], -1
	s_cmp_lg_u32 s22, 0
	s_mov_b64 s[24:25], -1
	s_nop 0
	s_cbranch_scc0 .LBB0_711
	s_and_saveexec_b64 s[26:27], s[24:25]
	s_cbranch_execz .LBB0_708
	s_branch .LBB0_714
